# v24 + FFN-up epilogue gelu as a staggered 4-row pipeline (transcendental ops spread between packed ops)
# speedup vs baseline: 1.0001x; 1.0001x over previous
; #define LAS __attribute__((address_space(3)))
; #define EPI_LANE() const int lane2 = fresh_lane(), fr = lane2 & 15, fq = lane2 >> 4
;     __device__ __forceinline__ void operator()(const f32x4 (&acc)[2][2][4][2], const Unit& u) const {
;     ...
;             EPI_LANE();
;             const float* cw = P->in[24] + (size_t)layer * 3 * F2; const float* cb = P->in[25] + (size_t)layer * F2;
;             bf16_t* eb = (bf16_t*)(P->ws + WS_EB);
;             const int ch0 = u.pn * 128 + wc * 32 + 8 * fq;
;             const float m0 = fr == 0 ? 1.f : 0.f, n0 = 1.f - m0, m15 = fr == 15 ? 1.f : 0.f, n15 = 1.f - m15;
;             LAS unsigned char* wl = lds + LDS_CW + wid * 1024;
;             { const int a_ = lane2 >> 3, q4 = (lane2 & 7) * 4;
;               const float* src = (a_ < 6 ? cw + (a_ >> 1) * F2 : cb) + (a_ & 1) * F + (unsigned)(u.pn * 128 + wc * 32 + q4);
;               const f32x4 wv = *(const f32x4*)src;
;               *(LAS f32x4*)(wl + lane2 * 16) = wv; }
;             asm volatile("s_waitcnt lgkmcnt(0)" ::: "memory");
; #pragma unroll
;             for (int ai = 0; ai < 2; ++ai) {
;                 const int rowb = u.pm * BM + ai * HALF + wr * 64, q = rowb >> 6;
;                 unsigned gq[4][4], pe[2][2][4];
; #pragma unroll
;                 for (int n = 0; n < 2; ++n) {
;                     f32x4 W[2][4];
; #pragma unroll
;                     for (int part = 0; part < 2; ++part)
; #pragma unroll
;                         for (int k = 0; k < 4; ++k) W[part][k] = *(const LAS f32x4*)(wl + (k * 2 + part) * 128 + (8 * fq + 4 * n) * 4);
; #pragma unroll
;                     for (int ep = 0; ep < 2; ++ep) {
;                         f32x2 cres[2][4];
; #pragma unroll
;                         for (int part = 0; part < 2; ++part) {
;                             const f32x2 w0 = (f32x2){W[part][0][2 * ep], W[part][0][2 * ep + 1]}, w1 = (f32x2){W[part][1][2 * ep], W[part][1][2 * ep + 1]};
;                             const f32x2 w2 = (f32x2){W[part][2][2 * ep], W[part][2][2 * ep + 1]}, bb = (f32x2){W[part][3][2 * ep], W[part][3][2 * ep + 1]};
;                             const f32x2 w0a = w0 * n0, w0b = w0 * m0, w2a = w2 * n15, w2b = w2 * m15;
;                             f32x2 X[4], R[4], L[4];
; #pragma unroll
;                             for (int m = 0; m < 4; ++m) { X[m] = (f32x2){acc[ai][part][m][n][2 * ep], acc[ai][part][m][n][2 * ep + 1]};
.LBB0_346:
	s_and_b64 vcc, exec, s[10:11]
	s_cbranch_vccz .LBB0_373
	s_cmp_eq_u32 s24, 3
	s_mov_b64 s[8:9], -1
	s_cbranch_scc0 .LBB0_373
	v_mbcnt_lo_u32_b32 v130, -1, 0
	v_mbcnt_hi_u32_b32 v130, -1, v130
	v_readlane_b32 s3, v255, 12
	v_and_b32_e32 v131, 15, v130
	v_lshrrev_b32_e32 v129, 4, v130
	v_mov_b32_e32 v134, 0xbdd2d3e8
	v_mov_b32_e32 v135, 0xbdd2d3e8
	v_mov_b32_e32 v136, 0xc0135761
	v_mov_b32_e32 v137, 0xc0135761
	v_lshl_add_u32 v132, v129, 5, s3
	ds_read_b64 v[202:203], v132 offset:0
	ds_read_b64 v[204:205], v132 offset:128
	ds_read_b64 v[206:207], v132 offset:256
	ds_read_b64 v[208:209], v132 offset:384
	ds_read_b64 v[210:211], v132 offset:512
	ds_read_b64 v[212:213], v132 offset:640
	ds_read_b64 v[214:215], v132 offset:768
	ds_read_b64 v[216:217], v132 offset:896
	v_cmp_eq_u32_e64 s[6:7], 0, v131
	v_cmp_eq_u32_e64 s[8:9], 15, v131
	v_cmp_ne_u32_e64 s[56:57], 0, v131
	v_cmp_ne_u32_e64 s[58:59], 15, v131
	s_lshl_b32 s1, s72, 7
	s_or_b32 s1, s1, s49
	v_lshl_add_u32 v133, v129, 3, s1
	s_lshl_b32 s1, s73, 8
	s_add_i32 s1, s1, s33
	v_lshl_add_u32 v128, v131, 2, s1
	v_mul_lo_u32 v128, v128, s78
	v_lshl_add_u32 v128, v133, 1, v128
	s_lshl_b32 s1, s73, 2
	s_lshr_b32 s3, s33, 6
	s_add_i32 s1, s1, s3
	s_mul_i32 s1, s1, 0x2c0
	v_lshrrev_b32_e32 v129, 3, v133
	v_add_lshl_u32 v129, v129, s1, 6
	v_add_u32_e32 v162, 0x5800, v129
	s_sub_u32 s10, s52, 0x5000000
	s_subb_u32 s11, s53, 0
	s_waitcnt lgkmcnt(0)
	v_pk_fma_f32 v[234:235], v[116:117], v[206:207], v[214:215]
	v_pk_fma_f32 v[236:237], v[100:101], v[206:207], v[214:215]
	v_pk_fma_f32 v[238:239], v[84:85], v[206:207], v[214:215]
	v_pk_fma_f32 v[240:241], v[52:53], v[206:207], v[214:215]
	v_pk_fma_f32 v[236:237], v[116:117], v[202:203], v[236:237]
	v_pk_fma_f32 v[238:239], v[100:101], v[202:203], v[238:239]
	v_pk_fma_f32 v[240:241], v[84:85], v[202:203], v[240:241]
	v_fmac_f32_dpp v234, v52, v202 row_shr:1 row_mask:0xf bank_mask:0xf bound_ctrl:1
	v_fmac_f32_dpp v235, v53, v203 row_shr:1 row_mask:0xf bank_mask:0xf bound_ctrl:1
	v_pk_fma_f32 v[236:237], v[84:85], v[210:211], v[236:237]
	v_pk_fma_f32 v[238:239], v[52:53], v[210:211], v[238:239]
	v_pk_fma_f32 v[234:235], v[100:101], v[210:211], v[234:235]
	v_fmac_f32_dpp v240, v116, v210 row_shl:1 row_mask:0xf bank_mask:0xf bound_ctrl:1
	v_fmac_f32_dpp v241, v117, v211 row_shl:1 row_mask:0xf bank_mask:0xf bound_ctrl:1
	v_cvt_pk_bf16_f32 v184, v234, v235
	v_cvt_pk_bf16_f32 v192, v240, v241
	v_pk_fma_f32 v[242:243], v[124:125], v[208:209], v[216:217]
	v_pk_fma_f32 v[244:245], v[108:109], v[208:209], v[216:217]
	v_pk_fma_f32 v[246:247], v[92:93], v[208:209], v[216:217]
	v_pk_fma_f32 v[248:249], v[68:69], v[208:209], v[216:217]
	v_pk_fma_f32 v[244:245], v[124:125], v[204:205], v[244:245]
	v_pk_fma_f32 v[246:247], v[108:109], v[204:205], v[246:247]
	v_pk_fma_f32 v[248:249], v[92:93], v[204:205], v[248:249]
	v_fmac_f32_dpp v242, v68, v204 row_shr:1 row_mask:0xf bank_mask:0xf bound_ctrl:1
	v_fmac_f32_dpp v243, v69, v205 row_shr:1 row_mask:0xf bank_mask:0xf bound_ctrl:1
	v_pk_fma_f32 v[244:245], v[92:93], v[212:213], v[244:245]
	v_pk_fma_f32 v[246:247], v[68:69], v[212:213], v[246:247]
	v_pk_fma_f32 v[242:243], v[108:109], v[212:213], v[242:243]
	v_fmac_f32_dpp v248, v124, v212 row_shl:1 row_mask:0xf bank_mask:0xf bound_ctrl:1
	v_fmac_f32_dpp v249, v125, v213 row_shl:1 row_mask:0xf bank_mask:0xf bound_ctrl:1
	v_cvt_pk_bf16_f32 v188, v242, v243
	v_cvt_pk_bf16_f32 v154, v248, v249
	ds_read_b64 v[202:203], v132 offset:8
	ds_read_b64 v[204:205], v132 offset:136
	ds_read_b64 v[206:207], v132 offset:264
	ds_read_b64 v[208:209], v132 offset:392
	ds_read_b64 v[210:211], v132 offset:520
	ds_read_b64 v[212:213], v132 offset:648
	ds_read_b64 v[214:215], v132 offset:776
	ds_read_b64 v[216:217], v132 offset:904
	v_pk_mul_f32 v[138:139], v[234:235], v[234:235]
	v_pk_fma_f32 v[138:139], v[138:139], v[134:135], v[136:137]
	v_pk_mul_f32 v[140:141], v[236:237], v[236:237]
	v_pk_mul_f32 v[138:139], v[234:235], v[138:139]
	v_pk_fma_f32 v[140:141], v[140:141], v[134:135], v[136:137]
	v_pk_mul_f32 v[142:143], v[238:239], v[238:239]
	v_exp_f32_e32 v138, v138
	v_pk_mul_f32 v[140:141], v[236:237], v[140:141]
	v_pk_fma_f32 v[142:143], v[142:143], v[134:135], v[136:137]
	v_pk_mul_f32 v[144:145], v[240:241], v[240:241]
	v_exp_f32_e32 v139, v139
	v_exp_f32_e32 v140, v140
	v_pk_mul_f32 v[142:143], v[238:239], v[142:143]
	v_pk_fma_f32 v[144:145], v[144:145], v[134:135], v[136:137]
	v_pk_mul_f32 v[146:147], v[234:235], v[242:243]
	v_exp_f32_e32 v141, v141
	v_exp_f32_e32 v142, v142
	v_pk_mul_f32 v[144:145], v[240:241], v[144:145]
	v_pk_add_f32 v[138:139], v[138:139], 1.0 op_sel_hi:[1,0]
	v_pk_mul_f32 v[148:149], v[236:237], v[244:245]
	v_exp_f32_e32 v143, v143
	v_exp_f32_e32 v144, v144
	v_rcp_f32_e32 v138, v138
	v_pk_add_f32 v[140:141], v[140:141], 1.0 op_sel_hi:[1,0]
	v_pk_mul_f32 v[150:151], v[238:239], v[246:247]
	v_exp_f32_e32 v145, v145
	v_rcp_f32_e32 v139, v139
	v_rcp_f32_e32 v140, v140
	v_pk_add_f32 v[142:143], v[142:143], 1.0 op_sel_hi:[1,0]
	v_pk_mul_f32 v[152:153], v[240:241], v[248:249]
	v_pk_mul_f32 v[146:147], v[146:147], v[138:139]
	v_rcp_f32_e32 v141, v141
	v_rcp_f32_e32 v142, v142
	v_pk_add_f32 v[144:145], v[144:145], 1.0 op_sel_hi:[1,0]
	v_cvt_pk_bf16_f32 v218, v146, v147
	v_pk_mul_f32 v[148:149], v[148:149], v[140:141]
	v_rcp_f32_e32 v143, v143
	v_rcp_f32_e32 v144, v144
	v_cvt_pk_bf16_f32 v222, v148, v149
	v_pk_mul_f32 v[150:151], v[150:151], v[142:143]
	v_rcp_f32_e32 v145, v145
	v_cvt_pk_bf16_f32 v226, v150, v151
	v_pk_mul_f32 v[152:153], v[152:153], v[144:145]
	v_cvt_pk_bf16_f32 v230, v152, v153
	s_waitcnt lgkmcnt(0)
; #define LAS __attribute__((address_space(3)))
;     __device__ __forceinline__ void operator()(const f32x4 (&acc)[2][2][4][2], const Unit& u) const {
;     ...
;                         for (int k = 0; k < 4; ++k) W[part][k] = *(const LAS f32x4*)(wl + (k * 2 + part) * 128 + (8 * fq + 4 * n) * 4);
; #pragma unroll
;                     for (int ep = 0; ep < 2; ++ep) {
;                         f32x2 cres[2][4];
; #pragma unroll
;                         for (int part = 0; part < 2; ++part) {
;                             const f32x2 w0 = (f32x2){W[part][0][2 * ep], W[part][0][2 * ep + 1]}, w1 = (f32x2){W[part][1][2 * ep], W[part][1][2 * ep + 1]};
;                             const f32x2 w2 = (f32x2){W[part][2][2 * ep], W[part][2][2 * ep + 1]}, bb = (f32x2){W[part][3][2 * ep], W[part][3][2 * ep + 1]};
;                             const f32x2 w0a = w0 * n0, w0b = w0 * m0, w2a = w2 * n15, w2b = w2 * m15;
;                             f32x2 X[4], R[4], L[4];
; #pragma unroll
;                             for (int m = 0; m < 4; ++m) { X[m] = (f32x2){acc[ai][part][m][n][2 * ep], acc[ai][part][m][n][2 * ep + 1]};
;                                 R[m] = (f32x2){dpp_prev(X[m].x), dpp_prev(X[m].y)}; L[m] = (f32x2){dpp_next(X[m].x), dpp_next(X[m].y)}; }
; #pragma unroll
;                             for (int m = 0; m < 4; ++m) {
;                                 f32x2 c = X[m] * w1 + bb; c = R[m] * w0a + c; c = L[m] * w2a + c;
;                                 if (m > 0) c = R[m > 0 ? m - 1 : 0] * w0b + c;
;                                 if (m < 3) c = L[m < 3 ? m + 1 : 3] * w2b + c;
;                                 cres[part][m] = c;
;                             }
;                             pe[0][part][n * 2 + ep] = cvt_pk_bf16(cres[part][0].x, cres[part][0].y);
;                             pe[1][part][n * 2 + ep] = cvt_pk_bf16(cres[part][3].x, cres[part][3].y);
;                             __builtin_amdgcn_sched_barrier(0);
;                         }
; #pragma unroll
;                         for (int m = 0; m < 4; ++m) {
;                             const f32x2 a = cres[0][m], v = cres[1][m];
;                             const f32x2 t = (a * a) * (-0.10294324f) + (-2.3022082f), z = a * t;
;                             f32x2 d; d.x = __builtin_amdgcn_exp2f(z.x) + 1.f; d.y = __builtin_amdgcn_exp2f(z.y) + 1.f;
	v_pk_fma_f32 v[234:235], v[118:119], v[206:207], v[214:215]
	v_pk_fma_f32 v[236:237], v[102:103], v[206:207], v[214:215]
	v_pk_fma_f32 v[238:239], v[86:87], v[206:207], v[214:215]
	v_pk_fma_f32 v[240:241], v[54:55], v[206:207], v[214:215]
	v_pk_fma_f32 v[236:237], v[118:119], v[202:203], v[236:237]
	v_pk_fma_f32 v[238:239], v[102:103], v[202:203], v[238:239]
	v_pk_fma_f32 v[240:241], v[86:87], v[202:203], v[240:241]
	v_fmac_f32_dpp v234, v54, v202 row_shr:1 row_mask:0xf bank_mask:0xf bound_ctrl:1
	v_fmac_f32_dpp v235, v55, v203 row_shr:1 row_mask:0xf bank_mask:0xf bound_ctrl:1
	v_pk_fma_f32 v[236:237], v[86:87], v[210:211], v[236:237]
	v_pk_fma_f32 v[238:239], v[54:55], v[210:211], v[238:239]
	v_pk_fma_f32 v[234:235], v[102:103], v[210:211], v[234:235]
	v_fmac_f32_dpp v240, v118, v210 row_shl:1 row_mask:0xf bank_mask:0xf bound_ctrl:1
	v_fmac_f32_dpp v241, v119, v211 row_shl:1 row_mask:0xf bank_mask:0xf bound_ctrl:1
	v_cvt_pk_bf16_f32 v185, v234, v235
	v_cvt_pk_bf16_f32 v193, v240, v241
	v_pk_fma_f32 v[242:243], v[126:127], v[208:209], v[216:217]
	v_pk_fma_f32 v[244:245], v[110:111], v[208:209], v[216:217]
	v_pk_fma_f32 v[246:247], v[94:95], v[208:209], v[216:217]
	v_pk_fma_f32 v[248:249], v[70:71], v[208:209], v[216:217]
	v_pk_fma_f32 v[244:245], v[126:127], v[204:205], v[244:245]
	v_pk_fma_f32 v[246:247], v[110:111], v[204:205], v[246:247]
	v_pk_fma_f32 v[248:249], v[94:95], v[204:205], v[248:249]
	v_fmac_f32_dpp v242, v70, v204 row_shr:1 row_mask:0xf bank_mask:0xf bound_ctrl:1
	v_fmac_f32_dpp v243, v71, v205 row_shr:1 row_mask:0xf bank_mask:0xf bound_ctrl:1
	v_pk_fma_f32 v[244:245], v[94:95], v[212:213], v[244:245]
	v_pk_fma_f32 v[246:247], v[70:71], v[212:213], v[246:247]
	v_pk_fma_f32 v[242:243], v[110:111], v[212:213], v[242:243]
	v_fmac_f32_dpp v248, v126, v212 row_shl:1 row_mask:0xf bank_mask:0xf bound_ctrl:1
	v_fmac_f32_dpp v249, v127, v213 row_shl:1 row_mask:0xf bank_mask:0xf bound_ctrl:1
	v_cvt_pk_bf16_f32 v189, v242, v243
	v_cvt_pk_bf16_f32 v155, v248, v249
	ds_read_b64 v[202:203], v132 offset:16
	ds_read_b64 v[204:205], v132 offset:144
	ds_read_b64 v[206:207], v132 offset:272
	ds_read_b64 v[208:209], v132 offset:400
	ds_read_b64 v[210:211], v132 offset:528
	ds_read_b64 v[212:213], v132 offset:656
	ds_read_b64 v[214:215], v132 offset:784
	ds_read_b64 v[216:217], v132 offset:912
	v_pk_mul_f32 v[138:139], v[234:235], v[234:235]
	v_pk_fma_f32 v[138:139], v[138:139], v[134:135], v[136:137]
	v_pk_mul_f32 v[140:141], v[236:237], v[236:237]
	v_pk_mul_f32 v[138:139], v[234:235], v[138:139]
	v_pk_fma_f32 v[140:141], v[140:141], v[134:135], v[136:137]
	v_pk_mul_f32 v[142:143], v[238:239], v[238:239]
	v_exp_f32_e32 v138, v138
	v_pk_mul_f32 v[140:141], v[236:237], v[140:141]
	v_pk_fma_f32 v[142:143], v[142:143], v[134:135], v[136:137]
	v_pk_mul_f32 v[144:145], v[240:241], v[240:241]
	v_exp_f32_e32 v139, v139
	v_exp_f32_e32 v140, v140
	v_pk_mul_f32 v[142:143], v[238:239], v[142:143]
	v_pk_fma_f32 v[144:145], v[144:145], v[134:135], v[136:137]
	v_pk_mul_f32 v[146:147], v[234:235], v[242:243]
	v_exp_f32_e32 v141, v141
	v_exp_f32_e32 v142, v142
	v_pk_mul_f32 v[144:145], v[240:241], v[144:145]
	v_pk_add_f32 v[138:139], v[138:139], 1.0 op_sel_hi:[1,0]
	v_pk_mul_f32 v[148:149], v[236:237], v[244:245]
	v_exp_f32_e32 v143, v143
	v_exp_f32_e32 v144, v144
	v_rcp_f32_e32 v138, v138
	v_pk_add_f32 v[140:141], v[140:141], 1.0 op_sel_hi:[1,0]
	v_pk_mul_f32 v[150:151], v[238:239], v[246:247]
	v_exp_f32_e32 v145, v145
	v_rcp_f32_e32 v139, v139
	v_rcp_f32_e32 v140, v140
	v_pk_add_f32 v[142:143], v[142:143], 1.0 op_sel_hi:[1,0]
	v_pk_mul_f32 v[152:153], v[240:241], v[248:249]
	v_pk_mul_f32 v[146:147], v[146:147], v[138:139]
	v_rcp_f32_e32 v141, v141
	v_rcp_f32_e32 v142, v142
	v_pk_add_f32 v[144:145], v[144:145], 1.0 op_sel_hi:[1,0]
	v_cvt_pk_bf16_f32 v219, v146, v147
	v_pk_mul_f32 v[148:149], v[148:149], v[140:141]
	v_rcp_f32_e32 v143, v143
	v_rcp_f32_e32 v144, v144
	v_cvt_pk_bf16_f32 v223, v148, v149
	v_pk_mul_f32 v[150:151], v[150:151], v[142:143]
	v_rcp_f32_e32 v145, v145
	v_cvt_pk_bf16_f32 v227, v150, v151
	v_pk_mul_f32 v[152:153], v[152:153], v[144:145]
	v_cvt_pk_bf16_f32 v231, v152, v153
	s_waitcnt lgkmcnt(0)
	v_pk_fma_f32 v[234:235], v[112:113], v[206:207], v[214:215]
	v_pk_fma_f32 v[236:237], v[96:97], v[206:207], v[214:215]
	v_pk_fma_f32 v[238:239], v[80:81], v[206:207], v[214:215]
	v_pk_fma_f32 v[240:241], v[48:49], v[206:207], v[214:215]
	v_pk_fma_f32 v[236:237], v[112:113], v[202:203], v[236:237]
	v_pk_fma_f32 v[238:239], v[96:97], v[202:203], v[238:239]
	v_pk_fma_f32 v[240:241], v[80:81], v[202:203], v[240:241]
	v_fmac_f32_dpp v234, v48, v202 row_shr:1 row_mask:0xf bank_mask:0xf bound_ctrl:1
	v_fmac_f32_dpp v235, v49, v203 row_shr:1 row_mask:0xf bank_mask:0xf bound_ctrl:1
	v_pk_fma_f32 v[236:237], v[80:81], v[210:211], v[236:237]
	v_pk_fma_f32 v[238:239], v[48:49], v[210:211], v[238:239]
	v_pk_fma_f32 v[234:235], v[96:97], v[210:211], v[234:235]
	v_fmac_f32_dpp v240, v112, v210 row_shl:1 row_mask:0xf bank_mask:0xf bound_ctrl:1
	v_fmac_f32_dpp v241, v113, v211 row_shl:1 row_mask:0xf bank_mask:0xf bound_ctrl:1
	v_cvt_pk_bf16_f32 v186, v234, v235
	v_cvt_pk_bf16_f32 v194, v240, v241
	v_pk_fma_f32 v[242:243], v[120:121], v[208:209], v[216:217]
	v_pk_fma_f32 v[244:245], v[104:105], v[208:209], v[216:217]
	v_pk_fma_f32 v[246:247], v[88:89], v[208:209], v[216:217]
	v_pk_fma_f32 v[248:249], v[60:61], v[208:209], v[216:217]
	v_pk_fma_f32 v[244:245], v[120:121], v[204:205], v[244:245]
	v_pk_fma_f32 v[246:247], v[104:105], v[204:205], v[246:247]
	v_pk_fma_f32 v[248:249], v[88:89], v[204:205], v[248:249]
	v_fmac_f32_dpp v242, v60, v204 row_shr:1 row_mask:0xf bank_mask:0xf bound_ctrl:1
; #define LAS __attribute__((address_space(3)))
;     __device__ __forceinline__ void operator()(const f32x4 (&acc)[2][2][4][2], const Unit& u) const {
;     ...
;                         for (int k = 0; k < 4; ++k) W[part][k] = *(const LAS f32x4*)(wl + (k * 2 + part) * 128 + (8 * fq + 4 * n) * 4);
; #pragma unroll
;                     for (int ep = 0; ep < 2; ++ep) {
;                         f32x2 cres[2][4];
; #pragma unroll
;                         for (int part = 0; part < 2; ++part) {
;                             const f32x2 w0 = (f32x2){W[part][0][2 * ep], W[part][0][2 * ep + 1]}, w1 = (f32x2){W[part][1][2 * ep], W[part][1][2 * ep + 1]};
;                             const f32x2 w2 = (f32x2){W[part][2][2 * ep], W[part][2][2 * ep + 1]}, bb = (f32x2){W[part][3][2 * ep], W[part][3][2 * ep + 1]};
;                             const f32x2 w0a = w0 * n0, w0b = w0 * m0, w2a = w2 * n15, w2b = w2 * m15;
;                             f32x2 X[4], R[4], L[4];
; #pragma unroll
;                             for (int m = 0; m < 4; ++m) { X[m] = (f32x2){acc[ai][part][m][n][2 * ep], acc[ai][part][m][n][2 * ep + 1]};
;                                 R[m] = (f32x2){dpp_prev(X[m].x), dpp_prev(X[m].y)}; L[m] = (f32x2){dpp_next(X[m].x), dpp_next(X[m].y)}; }
; #pragma unroll
;                             for (int m = 0; m < 4; ++m) {
;                                 f32x2 c = X[m] * w1 + bb; c = R[m] * w0a + c; c = L[m] * w2a + c;
;                                 if (m > 0) c = R[m > 0 ? m - 1 : 0] * w0b + c;
;                                 if (m < 3) c = L[m < 3 ? m + 1 : 3] * w2b + c;
;                                 cres[part][m] = c;
;                             }
;                             pe[0][part][n * 2 + ep] = cvt_pk_bf16(cres[part][0].x, cres[part][0].y);
;                             pe[1][part][n * 2 + ep] = cvt_pk_bf16(cres[part][3].x, cres[part][3].y);
;                             __builtin_amdgcn_sched_barrier(0);
;                         }
; #pragma unroll
;                         for (int m = 0; m < 4; ++m) {
;                             const f32x2 a = cres[0][m], v = cres[1][m];
;                             const f32x2 t = (a * a) * (-0.10294324f) + (-2.3022082f), z = a * t;
;                             f32x2 d; d.x = __builtin_amdgcn_exp2f(z.x) + 1.f; d.y = __builtin_amdgcn_exp2f(z.y) + 1.f;
	v_fmac_f32_dpp v243, v61, v205 row_shr:1 row_mask:0xf bank_mask:0xf bound_ctrl:1
	v_pk_fma_f32 v[244:245], v[88:89], v[212:213], v[244:245]
	v_pk_fma_f32 v[246:247], v[60:61], v[212:213], v[246:247]
	v_pk_fma_f32 v[242:243], v[104:105], v[212:213], v[242:243]
	v_fmac_f32_dpp v248, v120, v212 row_shl:1 row_mask:0xf bank_mask:0xf bound_ctrl:1
	v_fmac_f32_dpp v249, v121, v213 row_shl:1 row_mask:0xf bank_mask:0xf bound_ctrl:1
	v_cvt_pk_bf16_f32 v190, v242, v243
	v_cvt_pk_bf16_f32 v156, v248, v249
	ds_read_b64 v[202:203], v132 offset:24
	ds_read_b64 v[204:205], v132 offset:152
	ds_read_b64 v[206:207], v132 offset:280
	ds_read_b64 v[208:209], v132 offset:408
	ds_read_b64 v[210:211], v132 offset:536
	ds_read_b64 v[212:213], v132 offset:664
	ds_read_b64 v[214:215], v132 offset:792
	ds_read_b64 v[216:217], v132 offset:920
	v_pk_mul_f32 v[138:139], v[234:235], v[234:235]
	v_pk_fma_f32 v[138:139], v[138:139], v[134:135], v[136:137]
	v_pk_mul_f32 v[140:141], v[236:237], v[236:237]
	v_pk_mul_f32 v[138:139], v[234:235], v[138:139]
	v_pk_fma_f32 v[140:141], v[140:141], v[134:135], v[136:137]
	v_pk_mul_f32 v[142:143], v[238:239], v[238:239]
	v_exp_f32_e32 v138, v138
	v_pk_mul_f32 v[140:141], v[236:237], v[140:141]
	v_pk_fma_f32 v[142:143], v[142:143], v[134:135], v[136:137]
	v_pk_mul_f32 v[144:145], v[240:241], v[240:241]
	v_exp_f32_e32 v139, v139
	v_exp_f32_e32 v140, v140
	v_pk_mul_f32 v[142:143], v[238:239], v[142:143]
	v_pk_fma_f32 v[144:145], v[144:145], v[134:135], v[136:137]
	v_pk_mul_f32 v[146:147], v[234:235], v[242:243]
	v_exp_f32_e32 v141, v141
	v_exp_f32_e32 v142, v142
	v_pk_mul_f32 v[144:145], v[240:241], v[144:145]
	v_pk_add_f32 v[138:139], v[138:139], 1.0 op_sel_hi:[1,0]
	v_pk_mul_f32 v[148:149], v[236:237], v[244:245]
	v_exp_f32_e32 v143, v143
	v_exp_f32_e32 v144, v144
	v_rcp_f32_e32 v138, v138
	v_pk_add_f32 v[140:141], v[140:141], 1.0 op_sel_hi:[1,0]
	v_pk_mul_f32 v[150:151], v[238:239], v[246:247]
	v_exp_f32_e32 v145, v145
	v_rcp_f32_e32 v139, v139
	v_rcp_f32_e32 v140, v140
	v_pk_add_f32 v[142:143], v[142:143], 1.0 op_sel_hi:[1,0]
	v_pk_mul_f32 v[152:153], v[240:241], v[248:249]
	v_pk_mul_f32 v[146:147], v[146:147], v[138:139]
	v_rcp_f32_e32 v141, v141
	v_rcp_f32_e32 v142, v142
	v_pk_add_f32 v[144:145], v[144:145], 1.0 op_sel_hi:[1,0]
	v_cvt_pk_bf16_f32 v220, v146, v147
	v_pk_mul_f32 v[148:149], v[148:149], v[140:141]
	v_rcp_f32_e32 v143, v143
	v_rcp_f32_e32 v144, v144
	v_cvt_pk_bf16_f32 v224, v148, v149
	v_pk_mul_f32 v[150:151], v[150:151], v[142:143]
	v_rcp_f32_e32 v145, v145
	v_cvt_pk_bf16_f32 v228, v150, v151
	v_pk_mul_f32 v[152:153], v[152:153], v[144:145]
	v_cvt_pk_bf16_f32 v232, v152, v153
	s_waitcnt lgkmcnt(0)
	v_pk_fma_f32 v[234:235], v[114:115], v[206:207], v[214:215]
	v_pk_fma_f32 v[236:237], v[98:99], v[206:207], v[214:215]
	v_pk_fma_f32 v[238:239], v[82:83], v[206:207], v[214:215]
	v_pk_fma_f32 v[240:241], v[50:51], v[206:207], v[214:215]
	v_pk_fma_f32 v[236:237], v[114:115], v[202:203], v[236:237]
	v_pk_fma_f32 v[238:239], v[98:99], v[202:203], v[238:239]
	v_pk_fma_f32 v[240:241], v[82:83], v[202:203], v[240:241]
	v_fmac_f32_dpp v234, v50, v202 row_shr:1 row_mask:0xf bank_mask:0xf bound_ctrl:1
	v_fmac_f32_dpp v235, v51, v203 row_shr:1 row_mask:0xf bank_mask:0xf bound_ctrl:1
	v_pk_fma_f32 v[236:237], v[82:83], v[210:211], v[236:237]
	v_pk_fma_f32 v[238:239], v[50:51], v[210:211], v[238:239]
	v_pk_fma_f32 v[234:235], v[98:99], v[210:211], v[234:235]
	v_fmac_f32_dpp v240, v114, v210 row_shl:1 row_mask:0xf bank_mask:0xf bound_ctrl:1
	v_fmac_f32_dpp v241, v115, v211 row_shl:1 row_mask:0xf bank_mask:0xf bound_ctrl:1
	v_cvt_pk_bf16_f32 v187, v234, v235
	v_cvt_pk_bf16_f32 v195, v240, v241
	v_pk_fma_f32 v[242:243], v[122:123], v[208:209], v[216:217]
	v_pk_fma_f32 v[244:245], v[106:107], v[208:209], v[216:217]
	v_pk_fma_f32 v[246:247], v[90:91], v[208:209], v[216:217]
	v_pk_fma_f32 v[248:249], v[62:63], v[208:209], v[216:217]
	v_pk_fma_f32 v[244:245], v[122:123], v[204:205], v[244:245]
	v_pk_fma_f32 v[246:247], v[106:107], v[204:205], v[246:247]
	v_pk_fma_f32 v[248:249], v[90:91], v[204:205], v[248:249]
	v_fmac_f32_dpp v242, v62, v204 row_shr:1 row_mask:0xf bank_mask:0xf bound_ctrl:1
	v_fmac_f32_dpp v243, v63, v205 row_shr:1 row_mask:0xf bank_mask:0xf bound_ctrl:1
	v_pk_fma_f32 v[244:245], v[90:91], v[212:213], v[244:245]
	v_pk_fma_f32 v[246:247], v[62:63], v[212:213], v[246:247]
	v_pk_fma_f32 v[242:243], v[106:107], v[212:213], v[242:243]
	v_fmac_f32_dpp v248, v122, v212 row_shl:1 row_mask:0xf bank_mask:0xf bound_ctrl:1
	v_fmac_f32_dpp v249, v123, v213 row_shl:1 row_mask:0xf bank_mask:0xf bound_ctrl:1
	v_cvt_pk_bf16_f32 v191, v242, v243
	v_cvt_pk_bf16_f32 v157, v248, v249
	ds_read_b64 v[202:203], v132 offset:0
	ds_read_b64 v[204:205], v132 offset:128
	ds_read_b64 v[206:207], v132 offset:256
	ds_read_b64 v[208:209], v132 offset:384
	ds_read_b64 v[210:211], v132 offset:512
	ds_read_b64 v[212:213], v132 offset:640
	ds_read_b64 v[214:215], v132 offset:768
	ds_read_b64 v[216:217], v132 offset:896
	v_pk_mul_f32 v[138:139], v[234:235], v[234:235]
	v_pk_fma_f32 v[138:139], v[138:139], v[134:135], v[136:137]
	v_pk_mul_f32 v[140:141], v[236:237], v[236:237]
	v_pk_mul_f32 v[138:139], v[234:235], v[138:139]
	v_pk_fma_f32 v[140:141], v[140:141], v[134:135], v[136:137]
	v_pk_mul_f32 v[142:143], v[238:239], v[238:239]
	v_exp_f32_e32 v138, v138
	v_pk_mul_f32 v[140:141], v[236:237], v[140:141]
	v_pk_fma_f32 v[142:143], v[142:143], v[134:135], v[136:137]
	v_pk_mul_f32 v[144:145], v[240:241], v[240:241]
	v_exp_f32_e32 v139, v139
	v_exp_f32_e32 v140, v140
	v_pk_mul_f32 v[142:143], v[238:239], v[142:143]
	v_pk_fma_f32 v[144:145], v[144:145], v[134:135], v[136:137]
; #define LAS __attribute__((address_space(3)))
;     __device__ __forceinline__ void operator()(const f32x4 (&acc)[2][2][4][2], const Unit& u) const {
;     ...
;                         for (int k = 0; k < 4; ++k) W[part][k] = *(const LAS f32x4*)(wl + (k * 2 + part) * 128 + (8 * fq + 4 * n) * 4);
; #pragma unroll
;                     for (int ep = 0; ep < 2; ++ep) {
;                         f32x2 cres[2][4];
; #pragma unroll
;                         for (int part = 0; part < 2; ++part) {
;                             const f32x2 w0 = (f32x2){W[part][0][2 * ep], W[part][0][2 * ep + 1]}, w1 = (f32x2){W[part][1][2 * ep], W[part][1][2 * ep + 1]};
;                             const f32x2 w2 = (f32x2){W[part][2][2 * ep], W[part][2][2 * ep + 1]}, bb = (f32x2){W[part][3][2 * ep], W[part][3][2 * ep + 1]};
;                             const f32x2 w0a = w0 * n0, w0b = w0 * m0, w2a = w2 * n15, w2b = w2 * m15;
;                             f32x2 X[4], R[4], L[4];
; #pragma unroll
;                             for (int m = 0; m < 4; ++m) { X[m] = (f32x2){acc[ai][part][m][n][2 * ep], acc[ai][part][m][n][2 * ep + 1]};
;                                 R[m] = (f32x2){dpp_prev(X[m].x), dpp_prev(X[m].y)}; L[m] = (f32x2){dpp_next(X[m].x), dpp_next(X[m].y)}; }
; #pragma unroll
;                             for (int m = 0; m < 4; ++m) {
;                                 f32x2 c = X[m] * w1 + bb; c = R[m] * w0a + c; c = L[m] * w2a + c;
;                                 if (m > 0) c = R[m > 0 ? m - 1 : 0] * w0b + c;
;                                 if (m < 3) c = L[m < 3 ? m + 1 : 3] * w2b + c;
;                                 cres[part][m] = c;
;                             }
;                             pe[0][part][n * 2 + ep] = cvt_pk_bf16(cres[part][0].x, cres[part][0].y);
;                             pe[1][part][n * 2 + ep] = cvt_pk_bf16(cres[part][3].x, cres[part][3].y);
;                             __builtin_amdgcn_sched_barrier(0);
;                         }
; #pragma unroll
;                         for (int m = 0; m < 4; ++m) {
;                             const f32x2 a = cres[0][m], v = cres[1][m];
;                             const f32x2 t = (a * a) * (-0.10294324f) + (-2.3022082f), z = a * t;
;                             f32x2 d; d.x = __builtin_amdgcn_exp2f(z.x) + 1.f; d.y = __builtin_amdgcn_exp2f(z.y) + 1.f;
	v_pk_mul_f32 v[146:147], v[234:235], v[242:243]
	v_exp_f32_e32 v141, v141
	v_exp_f32_e32 v142, v142
	v_pk_mul_f32 v[144:145], v[240:241], v[144:145]
	v_pk_add_f32 v[138:139], v[138:139], 1.0 op_sel_hi:[1,0]
	v_pk_mul_f32 v[148:149], v[236:237], v[244:245]
	v_exp_f32_e32 v143, v143
	v_exp_f32_e32 v144, v144
	v_rcp_f32_e32 v138, v138
	v_pk_add_f32 v[140:141], v[140:141], 1.0 op_sel_hi:[1,0]
	v_pk_mul_f32 v[150:151], v[238:239], v[246:247]
	v_exp_f32_e32 v145, v145
	v_rcp_f32_e32 v139, v139
	v_rcp_f32_e32 v140, v140
	v_pk_add_f32 v[142:143], v[142:143], 1.0 op_sel_hi:[1,0]
	v_pk_mul_f32 v[152:153], v[240:241], v[248:249]
	v_pk_mul_f32 v[146:147], v[146:147], v[138:139]
	v_rcp_f32_e32 v141, v141
	v_rcp_f32_e32 v142, v142
	v_pk_add_f32 v[144:145], v[144:145], 1.0 op_sel_hi:[1,0]
	v_cvt_pk_bf16_f32 v221, v146, v147
	v_pk_mul_f32 v[148:149], v[148:149], v[140:141]
	v_rcp_f32_e32 v143, v143
	v_rcp_f32_e32 v144, v144
	v_cvt_pk_bf16_f32 v225, v148, v149
	v_pk_mul_f32 v[150:151], v[150:151], v[142:143]
	v_rcp_f32_e32 v145, v145
	v_cvt_pk_bf16_f32 v229, v150, v151
	v_pk_mul_f32 v[152:153], v[152:153], v[144:145]
	v_cvt_pk_bf16_f32 v233, v152, v153
	s_mov_b64 s[22:23], exec
	s_mov_b64 exec, s[6:7]
	v_cvt_pk_bf16_f32 v138, v116, v117
	v_cvt_pk_bf16_f32 v139, v118, v119
	v_cvt_pk_bf16_f32 v140, v112, v113
	v_cvt_pk_bf16_f32 v141, v114, v115
	v_cvt_pk_bf16_f32 v142, v124, v125
	v_cvt_pk_bf16_f32 v143, v126, v127
	v_cvt_pk_bf16_f32 v144, v120, v121
	v_cvt_pk_bf16_f32 v145, v122, v123
	global_store_dwordx4 v129, v[138:141], s[10:11]
	global_store_dwordx4 v129, v[142:145], s[10:11] offset:16
	global_store_dwordx4 v129, v[184:187], s[10:11] offset:32
	global_store_dwordx4 v129, v[188:191], s[10:11] offset:48
	s_mov_b64 exec, s[8:9]
	v_cvt_pk_bf16_f32 v146, v52, v53
	v_cvt_pk_bf16_f32 v147, v54, v55
	v_cvt_pk_bf16_f32 v148, v48, v49
	v_cvt_pk_bf16_f32 v149, v50, v51
	v_cvt_pk_bf16_f32 v150, v68, v69
	v_cvt_pk_bf16_f32 v151, v70, v71
	v_cvt_pk_bf16_f32 v152, v60, v61
	v_cvt_pk_bf16_f32 v153, v62, v63
	global_store_dwordx4 v162, v[146:149], s[10:11]
	global_store_dwordx4 v162, v[150:153], s[10:11] offset:16
	global_store_dwordx4 v162, v[192:195], s[10:11] offset:32
	global_store_dwordx4 v162, v[154:157], s[10:11] offset:48
	s_mov_b64 exec, s[56:57]
	global_store_dwordx4 v128, v[218:221], s[52:53]
	s_mov_b64 exec, s[22:23]
	v_add_u32_e32 v133, 0x1600, v128
	v_add_u32_e32 v130, 0x2c00, v128
	v_add_u32_e32 v131, 0x4200, v128
	global_store_dwordx4 v133, v[222:225], s[52:53]
	global_store_dwordx4 v130, v[226:229], s[52:53]
	s_mov_b64 exec, s[58:59]
	global_store_dwordx4 v131, v[230:233], s[52:53]
	s_mov_b64 exec, s[22:23]
	v_add_u32_e32 v128, 0xb0000, v128
	v_add_u32_e32 v129, 0x16000, v129
	v_add_u32_e32 v162, 0x16000, v162
	s_nop 1
	s_waitcnt lgkmcnt(0)
	v_pk_fma_f32 v[234:235], v[64:65], v[206:207], v[214:215]
	v_pk_fma_f32 v[236:237], v[36:37], v[206:207], v[214:215]
	v_pk_fma_f32 v[238:239], v[20:21], v[206:207], v[214:215]
	v_pk_fma_f32 v[240:241], v[4:5], v[206:207], v[214:215]
	v_pk_fma_f32 v[236:237], v[64:65], v[202:203], v[236:237]
	v_pk_fma_f32 v[238:239], v[36:37], v[202:203], v[238:239]
	v_pk_fma_f32 v[240:241], v[20:21], v[202:203], v[240:241]
	v_fmac_f32_dpp v234, v4, v202 row_shr:1 row_mask:0xf bank_mask:0xf bound_ctrl:1
	v_fmac_f32_dpp v235, v5, v203 row_shr:1 row_mask:0xf bank_mask:0xf bound_ctrl:1
	v_pk_fma_f32 v[236:237], v[20:21], v[210:211], v[236:237]
	v_pk_fma_f32 v[238:239], v[4:5], v[210:211], v[238:239]
	v_pk_fma_f32 v[234:235], v[36:37], v[210:211], v[234:235]
	v_fmac_f32_dpp v240, v64, v210 row_shl:1 row_mask:0xf bank_mask:0xf bound_ctrl:1
	v_fmac_f32_dpp v241, v65, v211 row_shl:1 row_mask:0xf bank_mask:0xf bound_ctrl:1
	v_cvt_pk_bf16_f32 v184, v234, v235
	v_cvt_pk_bf16_f32 v192, v240, v241
	v_pk_fma_f32 v[242:243], v[76:77], v[208:209], v[216:217]
	v_pk_fma_f32 v[244:245], v[44:45], v[208:209], v[216:217]
	v_pk_fma_f32 v[246:247], v[28:29], v[208:209], v[216:217]
	v_pk_fma_f32 v[248:249], v[12:13], v[208:209], v[216:217]
	v_pk_fma_f32 v[244:245], v[76:77], v[204:205], v[244:245]
	v_pk_fma_f32 v[246:247], v[44:45], v[204:205], v[246:247]
	v_pk_fma_f32 v[248:249], v[28:29], v[204:205], v[248:249]
	v_fmac_f32_dpp v242, v12, v204 row_shr:1 row_mask:0xf bank_mask:0xf bound_ctrl:1
	v_fmac_f32_dpp v243, v13, v205 row_shr:1 row_mask:0xf bank_mask:0xf bound_ctrl:1
	v_pk_fma_f32 v[244:245], v[28:29], v[212:213], v[244:245]
	v_pk_fma_f32 v[246:247], v[12:13], v[212:213], v[246:247]
	v_pk_fma_f32 v[242:243], v[44:45], v[212:213], v[242:243]
	v_fmac_f32_dpp v248, v76, v212 row_shl:1 row_mask:0xf bank_mask:0xf bound_ctrl:1
	v_fmac_f32_dpp v249, v77, v213 row_shl:1 row_mask:0xf bank_mask:0xf bound_ctrl:1
	v_cvt_pk_bf16_f32 v188, v242, v243
	v_cvt_pk_bf16_f32 v154, v248, v249
	ds_read_b64 v[202:203], v132 offset:8
	ds_read_b64 v[204:205], v132 offset:136
	ds_read_b64 v[206:207], v132 offset:264
	ds_read_b64 v[208:209], v132 offset:392
	ds_read_b64 v[210:211], v132 offset:520
	ds_read_b64 v[212:213], v132 offset:648
	ds_read_b64 v[214:215], v132 offset:776
	ds_read_b64 v[216:217], v132 offset:904
	v_pk_mul_f32 v[138:139], v[234:235], v[234:235]
	v_pk_fma_f32 v[138:139], v[138:139], v[134:135], v[136:137]
	v_pk_mul_f32 v[140:141], v[236:237], v[236:237]
	v_pk_mul_f32 v[138:139], v[234:235], v[138:139]
	v_pk_fma_f32 v[140:141], v[140:141], v[134:135], v[136:137]
	v_pk_mul_f32 v[142:143], v[238:239], v[238:239]
	v_exp_f32_e32 v138, v138
	v_pk_mul_f32 v[140:141], v[236:237], v[140:141]
	v_pk_fma_f32 v[142:143], v[142:143], v[134:135], v[136:137]
	v_pk_mul_f32 v[144:145], v[240:241], v[240:241]
	v_exp_f32_e32 v139, v139
	v_exp_f32_e32 v140, v140
	v_pk_mul_f32 v[142:143], v[238:239], v[142:143]
	v_pk_fma_f32 v[144:145], v[144:145], v[134:135], v[136:137]
	v_pk_mul_f32 v[146:147], v[234:235], v[242:243]
	v_exp_f32_e32 v141, v141
	v_exp_f32_e32 v142, v142
	v_pk_mul_f32 v[144:145], v[240:241], v[144:145]
	v_pk_add_f32 v[138:139], v[138:139], 1.0 op_sel_hi:[1,0]
	v_pk_mul_f32 v[148:149], v[236:237], v[244:245]
	v_exp_f32_e32 v143, v143
	v_exp_f32_e32 v144, v144
	v_rcp_f32_e32 v138, v138
	v_pk_add_f32 v[140:141], v[140:141], 1.0 op_sel_hi:[1,0]
	v_pk_mul_f32 v[150:151], v[238:239], v[246:247]
	v_exp_f32_e32 v145, v145
	v_rcp_f32_e32 v139, v139
	v_rcp_f32_e32 v140, v140
	v_pk_add_f32 v[142:143], v[142:143], 1.0 op_sel_hi:[1,0]
	v_pk_mul_f32 v[152:153], v[240:241], v[248:249]
	v_pk_mul_f32 v[146:147], v[146:147], v[138:139]
	v_rcp_f32_e32 v141, v141
	v_rcp_f32_e32 v142, v142
	v_pk_add_f32 v[144:145], v[144:145], 1.0 op_sel_hi:[1,0]
	v_cvt_pk_bf16_f32 v218, v146, v147
	v_pk_mul_f32 v[148:149], v[148:149], v[140:141]
	v_rcp_f32_e32 v143, v143
	v_rcp_f32_e32 v144, v144
	v_cvt_pk_bf16_f32 v222, v148, v149
	v_pk_mul_f32 v[150:151], v[150:151], v[142:143]
	v_rcp_f32_e32 v145, v145
	v_cvt_pk_bf16_f32 v226, v150, v151
	v_pk_mul_f32 v[152:153], v[152:153], v[144:145]
	v_cvt_pk_bf16_f32 v230, v152, v153
	s_waitcnt lgkmcnt(0)
; #define LAS __attribute__((address_space(3)))
;     __device__ __forceinline__ void operator()(const f32x4 (&acc)[2][2][4][2], const Unit& u) const {
;     ...
;                         for (int k = 0; k < 4; ++k) W[part][k] = *(const LAS f32x4*)(wl + (k * 2 + part) * 128 + (8 * fq + 4 * n) * 4);
; #pragma unroll
;                     for (int ep = 0; ep < 2; ++ep) {
;                         f32x2 cres[2][4];
; #pragma unroll
;                         for (int part = 0; part < 2; ++part) {
;                             const f32x2 w0 = (f32x2){W[part][0][2 * ep], W[part][0][2 * ep + 1]}, w1 = (f32x2){W[part][1][2 * ep], W[part][1][2 * ep + 1]};
;                             const f32x2 w2 = (f32x2){W[part][2][2 * ep], W[part][2][2 * ep + 1]}, bb = (f32x2){W[part][3][2 * ep], W[part][3][2 * ep + 1]};
;                             const f32x2 w0a = w0 * n0, w0b = w0 * m0, w2a = w2 * n15, w2b = w2 * m15;
;                             f32x2 X[4], R[4], L[4];
; #pragma unroll
;                             for (int m = 0; m < 4; ++m) { X[m] = (f32x2){acc[ai][part][m][n][2 * ep], acc[ai][part][m][n][2 * ep + 1]};
;                                 R[m] = (f32x2){dpp_prev(X[m].x), dpp_prev(X[m].y)}; L[m] = (f32x2){dpp_next(X[m].x), dpp_next(X[m].y)}; }
; #pragma unroll
;                             for (int m = 0; m < 4; ++m) {
;                                 f32x2 c = X[m] * w1 + bb; c = R[m] * w0a + c; c = L[m] * w2a + c;
;                                 if (m > 0) c = R[m > 0 ? m - 1 : 0] * w0b + c;
;                                 if (m < 3) c = L[m < 3 ? m + 1 : 3] * w2b + c;
;                                 cres[part][m] = c;
;                             }
;                             pe[0][part][n * 2 + ep] = cvt_pk_bf16(cres[part][0].x, cres[part][0].y);
;                             pe[1][part][n * 2 + ep] = cvt_pk_bf16(cres[part][3].x, cres[part][3].y);
;                             __builtin_amdgcn_sched_barrier(0);
;                         }
; #pragma unroll
;                         for (int m = 0; m < 4; ++m) {
;                             const f32x2 a = cres[0][m], v = cres[1][m];
;                             const f32x2 t = (a * a) * (-0.10294324f) + (-2.3022082f), z = a * t;
;                             f32x2 d; d.x = __builtin_amdgcn_exp2f(z.x) + 1.f; d.y = __builtin_amdgcn_exp2f(z.y) + 1.f;
	v_pk_fma_f32 v[234:235], v[66:67], v[206:207], v[214:215]
	v_pk_fma_f32 v[236:237], v[38:39], v[206:207], v[214:215]
	v_pk_fma_f32 v[238:239], v[22:23], v[206:207], v[214:215]
	v_pk_fma_f32 v[240:241], v[6:7], v[206:207], v[214:215]
	v_pk_fma_f32 v[236:237], v[66:67], v[202:203], v[236:237]
	v_pk_fma_f32 v[238:239], v[38:39], v[202:203], v[238:239]
	v_pk_fma_f32 v[240:241], v[22:23], v[202:203], v[240:241]
	v_fmac_f32_dpp v234, v6, v202 row_shr:1 row_mask:0xf bank_mask:0xf bound_ctrl:1
	v_fmac_f32_dpp v235, v7, v203 row_shr:1 row_mask:0xf bank_mask:0xf bound_ctrl:1
	v_pk_fma_f32 v[236:237], v[22:23], v[210:211], v[236:237]
	v_pk_fma_f32 v[238:239], v[6:7], v[210:211], v[238:239]
	v_pk_fma_f32 v[234:235], v[38:39], v[210:211], v[234:235]
	v_fmac_f32_dpp v240, v66, v210 row_shl:1 row_mask:0xf bank_mask:0xf bound_ctrl:1
	v_fmac_f32_dpp v241, v67, v211 row_shl:1 row_mask:0xf bank_mask:0xf bound_ctrl:1
	v_cvt_pk_bf16_f32 v185, v234, v235
	v_cvt_pk_bf16_f32 v193, v240, v241
	v_pk_fma_f32 v[242:243], v[78:79], v[208:209], v[216:217]
	v_pk_fma_f32 v[244:245], v[46:47], v[208:209], v[216:217]
	v_pk_fma_f32 v[246:247], v[30:31], v[208:209], v[216:217]
	v_pk_fma_f32 v[248:249], v[14:15], v[208:209], v[216:217]
	v_pk_fma_f32 v[244:245], v[78:79], v[204:205], v[244:245]
	v_pk_fma_f32 v[246:247], v[46:47], v[204:205], v[246:247]
	v_pk_fma_f32 v[248:249], v[30:31], v[204:205], v[248:249]
	v_fmac_f32_dpp v242, v14, v204 row_shr:1 row_mask:0xf bank_mask:0xf bound_ctrl:1
	v_fmac_f32_dpp v243, v15, v205 row_shr:1 row_mask:0xf bank_mask:0xf bound_ctrl:1
	v_pk_fma_f32 v[244:245], v[30:31], v[212:213], v[244:245]
	v_pk_fma_f32 v[246:247], v[14:15], v[212:213], v[246:247]
	v_pk_fma_f32 v[242:243], v[46:47], v[212:213], v[242:243]
	v_fmac_f32_dpp v248, v78, v212 row_shl:1 row_mask:0xf bank_mask:0xf bound_ctrl:1
	v_fmac_f32_dpp v249, v79, v213 row_shl:1 row_mask:0xf bank_mask:0xf bound_ctrl:1
	v_cvt_pk_bf16_f32 v189, v242, v243
	v_cvt_pk_bf16_f32 v155, v248, v249
	ds_read_b64 v[202:203], v132 offset:16
	ds_read_b64 v[204:205], v132 offset:144
	ds_read_b64 v[206:207], v132 offset:272
	ds_read_b64 v[208:209], v132 offset:400
	ds_read_b64 v[210:211], v132 offset:528
	ds_read_b64 v[212:213], v132 offset:656
	ds_read_b64 v[214:215], v132 offset:784
	ds_read_b64 v[216:217], v132 offset:912
	v_pk_mul_f32 v[138:139], v[234:235], v[234:235]
	v_pk_fma_f32 v[138:139], v[138:139], v[134:135], v[136:137]
	v_pk_mul_f32 v[140:141], v[236:237], v[236:237]
	v_pk_mul_f32 v[138:139], v[234:235], v[138:139]
	v_pk_fma_f32 v[140:141], v[140:141], v[134:135], v[136:137]
	v_pk_mul_f32 v[142:143], v[238:239], v[238:239]
	v_exp_f32_e32 v138, v138
	v_pk_mul_f32 v[140:141], v[236:237], v[140:141]
	v_pk_fma_f32 v[142:143], v[142:143], v[134:135], v[136:137]
	v_pk_mul_f32 v[144:145], v[240:241], v[240:241]
	v_exp_f32_e32 v139, v139
	v_exp_f32_e32 v140, v140
	v_pk_mul_f32 v[142:143], v[238:239], v[142:143]
	v_pk_fma_f32 v[144:145], v[144:145], v[134:135], v[136:137]
	v_pk_mul_f32 v[146:147], v[234:235], v[242:243]
	v_exp_f32_e32 v141, v141
	v_exp_f32_e32 v142, v142
	v_pk_mul_f32 v[144:145], v[240:241], v[144:145]
	v_pk_add_f32 v[138:139], v[138:139], 1.0 op_sel_hi:[1,0]
	v_pk_mul_f32 v[148:149], v[236:237], v[244:245]
	v_exp_f32_e32 v143, v143
	v_exp_f32_e32 v144, v144
	v_rcp_f32_e32 v138, v138
	v_pk_add_f32 v[140:141], v[140:141], 1.0 op_sel_hi:[1,0]
	v_pk_mul_f32 v[150:151], v[238:239], v[246:247]
	v_exp_f32_e32 v145, v145
	v_rcp_f32_e32 v139, v139
	v_rcp_f32_e32 v140, v140
	v_pk_add_f32 v[142:143], v[142:143], 1.0 op_sel_hi:[1,0]
	v_pk_mul_f32 v[152:153], v[240:241], v[248:249]
	v_pk_mul_f32 v[146:147], v[146:147], v[138:139]
	v_rcp_f32_e32 v141, v141
	v_rcp_f32_e32 v142, v142
	v_pk_add_f32 v[144:145], v[144:145], 1.0 op_sel_hi:[1,0]
	v_cvt_pk_bf16_f32 v219, v146, v147
	v_pk_mul_f32 v[148:149], v[148:149], v[140:141]
	v_rcp_f32_e32 v143, v143
	v_rcp_f32_e32 v144, v144
	v_cvt_pk_bf16_f32 v223, v148, v149
	v_pk_mul_f32 v[150:151], v[150:151], v[142:143]
	v_rcp_f32_e32 v145, v145
	v_cvt_pk_bf16_f32 v227, v150, v151
	v_pk_mul_f32 v[152:153], v[152:153], v[144:145]
	v_cvt_pk_bf16_f32 v231, v152, v153
	s_waitcnt lgkmcnt(0)
	v_pk_fma_f32 v[234:235], v[56:57], v[206:207], v[214:215]
	v_pk_fma_f32 v[236:237], v[32:33], v[206:207], v[214:215]
	v_pk_fma_f32 v[238:239], v[16:17], v[206:207], v[214:215]
	v_pk_fma_f32 v[240:241], v[0:1], v[206:207], v[214:215]
	v_pk_fma_f32 v[236:237], v[56:57], v[202:203], v[236:237]
	v_pk_fma_f32 v[238:239], v[32:33], v[202:203], v[238:239]
	v_pk_fma_f32 v[240:241], v[16:17], v[202:203], v[240:241]
	v_fmac_f32_dpp v234, v0, v202 row_shr:1 row_mask:0xf bank_mask:0xf bound_ctrl:1
	v_fmac_f32_dpp v235, v1, v203 row_shr:1 row_mask:0xf bank_mask:0xf bound_ctrl:1
	v_pk_fma_f32 v[236:237], v[16:17], v[210:211], v[236:237]
	v_pk_fma_f32 v[238:239], v[0:1], v[210:211], v[238:239]
	v_pk_fma_f32 v[234:235], v[32:33], v[210:211], v[234:235]
	v_fmac_f32_dpp v240, v56, v210 row_shl:1 row_mask:0xf bank_mask:0xf bound_ctrl:1
	v_fmac_f32_dpp v241, v57, v211 row_shl:1 row_mask:0xf bank_mask:0xf bound_ctrl:1
	v_cvt_pk_bf16_f32 v186, v234, v235
	v_cvt_pk_bf16_f32 v194, v240, v241
	v_pk_fma_f32 v[242:243], v[72:73], v[208:209], v[216:217]
	v_pk_fma_f32 v[244:245], v[40:41], v[208:209], v[216:217]
	v_pk_fma_f32 v[246:247], v[24:25], v[208:209], v[216:217]
	v_pk_fma_f32 v[248:249], v[8:9], v[208:209], v[216:217]
	v_pk_fma_f32 v[244:245], v[72:73], v[204:205], v[244:245]
	v_pk_fma_f32 v[246:247], v[40:41], v[204:205], v[246:247]
	v_pk_fma_f32 v[248:249], v[24:25], v[204:205], v[248:249]
	v_fmac_f32_dpp v242, v8, v204 row_shr:1 row_mask:0xf bank_mask:0xf bound_ctrl:1
; #define LAS __attribute__((address_space(3)))
;     __device__ __forceinline__ void operator()(const f32x4 (&acc)[2][2][4][2], const Unit& u) const {
;     ...
;                         for (int k = 0; k < 4; ++k) W[part][k] = *(const LAS f32x4*)(wl + (k * 2 + part) * 128 + (8 * fq + 4 * n) * 4);
; #pragma unroll
;                     for (int ep = 0; ep < 2; ++ep) {
;                         f32x2 cres[2][4];
; #pragma unroll
;                         for (int part = 0; part < 2; ++part) {
;                             const f32x2 w0 = (f32x2){W[part][0][2 * ep], W[part][0][2 * ep + 1]}, w1 = (f32x2){W[part][1][2 * ep], W[part][1][2 * ep + 1]};
;                             const f32x2 w2 = (f32x2){W[part][2][2 * ep], W[part][2][2 * ep + 1]}, bb = (f32x2){W[part][3][2 * ep], W[part][3][2 * ep + 1]};
;                             const f32x2 w0a = w0 * n0, w0b = w0 * m0, w2a = w2 * n15, w2b = w2 * m15;
;                             f32x2 X[4], R[4], L[4];
; #pragma unroll
;                             for (int m = 0; m < 4; ++m) { X[m] = (f32x2){acc[ai][part][m][n][2 * ep], acc[ai][part][m][n][2 * ep + 1]};
;                                 R[m] = (f32x2){dpp_prev(X[m].x), dpp_prev(X[m].y)}; L[m] = (f32x2){dpp_next(X[m].x), dpp_next(X[m].y)}; }
; #pragma unroll
;                             for (int m = 0; m < 4; ++m) {
;                                 f32x2 c = X[m] * w1 + bb; c = R[m] * w0a + c; c = L[m] * w2a + c;
;                                 if (m > 0) c = R[m > 0 ? m - 1 : 0] * w0b + c;
;                                 if (m < 3) c = L[m < 3 ? m + 1 : 3] * w2b + c;
;                                 cres[part][m] = c;
;                             }
;                             pe[0][part][n * 2 + ep] = cvt_pk_bf16(cres[part][0].x, cres[part][0].y);
;                             pe[1][part][n * 2 + ep] = cvt_pk_bf16(cres[part][3].x, cres[part][3].y);
;                             __builtin_amdgcn_sched_barrier(0);
;                         }
; #pragma unroll
;                         for (int m = 0; m < 4; ++m) {
;                             const f32x2 a = cres[0][m], v = cres[1][m];
;                             const f32x2 t = (a * a) * (-0.10294324f) + (-2.3022082f), z = a * t;
;                             f32x2 d; d.x = __builtin_amdgcn_exp2f(z.x) + 1.f; d.y = __builtin_amdgcn_exp2f(z.y) + 1.f;
	v_fmac_f32_dpp v243, v9, v205 row_shr:1 row_mask:0xf bank_mask:0xf bound_ctrl:1
	v_pk_fma_f32 v[244:245], v[24:25], v[212:213], v[244:245]
	v_pk_fma_f32 v[246:247], v[8:9], v[212:213], v[246:247]
	v_pk_fma_f32 v[242:243], v[40:41], v[212:213], v[242:243]
	v_fmac_f32_dpp v248, v72, v212 row_shl:1 row_mask:0xf bank_mask:0xf bound_ctrl:1
	v_fmac_f32_dpp v249, v73, v213 row_shl:1 row_mask:0xf bank_mask:0xf bound_ctrl:1
	v_cvt_pk_bf16_f32 v190, v242, v243
	v_cvt_pk_bf16_f32 v156, v248, v249
	ds_read_b64 v[202:203], v132 offset:24
	ds_read_b64 v[204:205], v132 offset:152
	ds_read_b64 v[206:207], v132 offset:280
	ds_read_b64 v[208:209], v132 offset:408
	ds_read_b64 v[210:211], v132 offset:536
	ds_read_b64 v[212:213], v132 offset:664
	ds_read_b64 v[214:215], v132 offset:792
	ds_read_b64 v[216:217], v132 offset:920
	v_pk_mul_f32 v[138:139], v[234:235], v[234:235]
	v_pk_fma_f32 v[138:139], v[138:139], v[134:135], v[136:137]
	v_pk_mul_f32 v[140:141], v[236:237], v[236:237]
	v_pk_mul_f32 v[138:139], v[234:235], v[138:139]
	v_pk_fma_f32 v[140:141], v[140:141], v[134:135], v[136:137]
	v_pk_mul_f32 v[142:143], v[238:239], v[238:239]
	v_exp_f32_e32 v138, v138
	v_pk_mul_f32 v[140:141], v[236:237], v[140:141]
	v_pk_fma_f32 v[142:143], v[142:143], v[134:135], v[136:137]
	v_pk_mul_f32 v[144:145], v[240:241], v[240:241]
	v_exp_f32_e32 v139, v139
	v_exp_f32_e32 v140, v140
	v_pk_mul_f32 v[142:143], v[238:239], v[142:143]
	v_pk_fma_f32 v[144:145], v[144:145], v[134:135], v[136:137]
	v_pk_mul_f32 v[146:147], v[234:235], v[242:243]
	v_exp_f32_e32 v141, v141
	v_exp_f32_e32 v142, v142
	v_pk_mul_f32 v[144:145], v[240:241], v[144:145]
	v_pk_add_f32 v[138:139], v[138:139], 1.0 op_sel_hi:[1,0]
	v_pk_mul_f32 v[148:149], v[236:237], v[244:245]
	v_exp_f32_e32 v143, v143
	v_exp_f32_e32 v144, v144
	v_rcp_f32_e32 v138, v138
	v_pk_add_f32 v[140:141], v[140:141], 1.0 op_sel_hi:[1,0]
	v_pk_mul_f32 v[150:151], v[238:239], v[246:247]
	v_exp_f32_e32 v145, v145
	v_rcp_f32_e32 v139, v139
	v_rcp_f32_e32 v140, v140
	v_pk_add_f32 v[142:143], v[142:143], 1.0 op_sel_hi:[1,0]
	v_pk_mul_f32 v[152:153], v[240:241], v[248:249]
	v_pk_mul_f32 v[146:147], v[146:147], v[138:139]
	v_rcp_f32_e32 v141, v141
	v_rcp_f32_e32 v142, v142
	v_pk_add_f32 v[144:145], v[144:145], 1.0 op_sel_hi:[1,0]
	v_cvt_pk_bf16_f32 v220, v146, v147
	v_pk_mul_f32 v[148:149], v[148:149], v[140:141]
	v_rcp_f32_e32 v143, v143
	v_rcp_f32_e32 v144, v144
	v_cvt_pk_bf16_f32 v224, v148, v149
	v_pk_mul_f32 v[150:151], v[150:151], v[142:143]
	v_rcp_f32_e32 v145, v145
	v_cvt_pk_bf16_f32 v228, v150, v151
	v_pk_mul_f32 v[152:153], v[152:153], v[144:145]
	v_cvt_pk_bf16_f32 v232, v152, v153
	s_waitcnt lgkmcnt(0)
; __device__ __forceinline__ unsigned cvt_pk_bf16(float lo, float hi) { unsigned r; asm volatile("v_cvt_pk_bf16_f32 %0, %1, %2" : "=v"(r) : "v"(lo), "v"(hi)); return r; }
;     __device__ __forceinline__ void operator()(const f32x4 (&acc)[2][2][4][2], const Unit& u) const {
;     ...
;                         for (int m = 0; m < 4; ++m) {
;                             const f32x2 a = cres[0][m], v = cres[1][m];
;                             const f32x2 t = (a * a) * (-0.10294324f) + (-2.3022082f), z = a * t;
;                             f32x2 d; d.x = __builtin_amdgcn_exp2f(z.x) + 1.f; d.y = __builtin_amdgcn_exp2f(z.y) + 1.f;
;                             f32x2 r; r.x = __builtin_amdgcn_rcpf(d.x); r.y = __builtin_amdgcn_rcpf(d.y);
;                             const f32x2 o = (a * v) * r;
;                             gq[m][n * 2 + ep] = cvt_pk_bf16(o.x, o.y);
;                         }
;                         __builtin_amdgcn_sched_barrier(0);
;                     }
;                 }
;                 if (fr == 0 || fr == 15) {
;                     const bool sel = fr == 15;
;                     bf16_t* ep_ = eb + (unsigned)((((q * 2 + (sel ? 1 : 0)) * 352 + (ch0 >> 3)) * 4) * 8);
; #pragma unroll
;                     for (int part = 0; part < 2; ++part) {
;                         float rw[8];
; #pragma unroll
;                         for (int e = 0; e < 8; ++e) rw[e] = sel ? acc[ai][part][3][e >> 2][e & 3] : acc[ai][part][0][e >> 2][e & 3];
;                         *(u32x4*)(ep_ + part * 8) = pack8(rw);
;                         *(u32x4*)(ep_ + (2 + part) * 8) = (u32x4){sel ? pe[1][part][0] : pe[0][part][0], sel ? pe[1][part][1] : pe[0][part][1], sel ? pe[1][part][2] : pe[0][part][2], sel ? pe[1][part][3] : pe[0][part][3]};
;                     }
;                 }
; #pragma unroll
;                 for (int m = 0; m < 4; ++m) {
;                     const bool edge = (m == 0 && fr == 0) || (m == 3 && fr == 15);
;                     if (!edge) *(u32x4*)((bf16_t*)O + (unsigned)((rowb + m * 16 + fr) * F + ch0)) = (u32x4){gq[m][0], gq[m][1], gq[m][2], gq[m][3]};
;                 }
	v_pk_fma_f32 v[234:235], v[58:59], v[206:207], v[214:215]
	v_pk_fma_f32 v[236:237], v[34:35], v[206:207], v[214:215]
	v_pk_fma_f32 v[238:239], v[18:19], v[206:207], v[214:215]
	v_pk_fma_f32 v[240:241], v[2:3], v[206:207], v[214:215]
	v_pk_fma_f32 v[236:237], v[58:59], v[202:203], v[236:237]
	v_pk_fma_f32 v[238:239], v[34:35], v[202:203], v[238:239]
	v_pk_fma_f32 v[240:241], v[18:19], v[202:203], v[240:241]
	v_fmac_f32_dpp v234, v2, v202 row_shr:1 row_mask:0xf bank_mask:0xf bound_ctrl:1
	v_fmac_f32_dpp v235, v3, v203 row_shr:1 row_mask:0xf bank_mask:0xf bound_ctrl:1
	v_pk_fma_f32 v[236:237], v[18:19], v[210:211], v[236:237]
	v_pk_fma_f32 v[238:239], v[2:3], v[210:211], v[238:239]
	v_pk_fma_f32 v[234:235], v[34:35], v[210:211], v[234:235]
	v_fmac_f32_dpp v240, v58, v210 row_shl:1 row_mask:0xf bank_mask:0xf bound_ctrl:1
	v_fmac_f32_dpp v241, v59, v211 row_shl:1 row_mask:0xf bank_mask:0xf bound_ctrl:1
	v_cvt_pk_bf16_f32 v187, v234, v235
	v_cvt_pk_bf16_f32 v195, v240, v241
	v_pk_fma_f32 v[242:243], v[74:75], v[208:209], v[216:217]
	v_pk_fma_f32 v[244:245], v[42:43], v[208:209], v[216:217]
	v_pk_fma_f32 v[246:247], v[26:27], v[208:209], v[216:217]
	v_pk_fma_f32 v[248:249], v[10:11], v[208:209], v[216:217]
	v_pk_fma_f32 v[244:245], v[74:75], v[204:205], v[244:245]
	v_pk_fma_f32 v[246:247], v[42:43], v[204:205], v[246:247]
	v_pk_fma_f32 v[248:249], v[26:27], v[204:205], v[248:249]
	v_fmac_f32_dpp v242, v10, v204 row_shr:1 row_mask:0xf bank_mask:0xf bound_ctrl:1
	v_fmac_f32_dpp v243, v11, v205 row_shr:1 row_mask:0xf bank_mask:0xf bound_ctrl:1
	v_pk_fma_f32 v[244:245], v[26:27], v[212:213], v[244:245]
	v_pk_fma_f32 v[246:247], v[10:11], v[212:213], v[246:247]
	v_pk_fma_f32 v[242:243], v[42:43], v[212:213], v[242:243]
	v_fmac_f32_dpp v248, v74, v212 row_shl:1 row_mask:0xf bank_mask:0xf bound_ctrl:1
	v_fmac_f32_dpp v249, v75, v213 row_shl:1 row_mask:0xf bank_mask:0xf bound_ctrl:1
	v_cvt_pk_bf16_f32 v191, v242, v243
	v_cvt_pk_bf16_f32 v157, v248, v249
	v_pk_mul_f32 v[138:139], v[234:235], v[234:235]
	v_pk_fma_f32 v[138:139], v[138:139], v[134:135], v[136:137]
	v_pk_mul_f32 v[140:141], v[236:237], v[236:237]
	v_pk_mul_f32 v[138:139], v[234:235], v[138:139]
	v_pk_fma_f32 v[140:141], v[140:141], v[134:135], v[136:137]
	v_pk_mul_f32 v[142:143], v[238:239], v[238:239]
	v_exp_f32_e32 v138, v138
	v_pk_mul_f32 v[140:141], v[236:237], v[140:141]
	v_pk_fma_f32 v[142:143], v[142:143], v[134:135], v[136:137]
	v_pk_mul_f32 v[144:145], v[240:241], v[240:241]
	v_exp_f32_e32 v139, v139
	v_exp_f32_e32 v140, v140
	v_pk_mul_f32 v[142:143], v[238:239], v[142:143]
	v_pk_fma_f32 v[144:145], v[144:145], v[134:135], v[136:137]
	v_pk_mul_f32 v[146:147], v[234:235], v[242:243]
	v_exp_f32_e32 v141, v141
	v_exp_f32_e32 v142, v142
	v_pk_mul_f32 v[144:145], v[240:241], v[144:145]
	v_pk_add_f32 v[138:139], v[138:139], 1.0 op_sel_hi:[1,0]
	v_pk_mul_f32 v[148:149], v[236:237], v[244:245]
	v_exp_f32_e32 v143, v143
	v_exp_f32_e32 v144, v144
	v_rcp_f32_e32 v138, v138
	v_pk_add_f32 v[140:141], v[140:141], 1.0 op_sel_hi:[1,0]
	v_pk_mul_f32 v[150:151], v[238:239], v[246:247]
	v_exp_f32_e32 v145, v145
	v_rcp_f32_e32 v139, v139
	v_rcp_f32_e32 v140, v140
	v_pk_add_f32 v[142:143], v[142:143], 1.0 op_sel_hi:[1,0]
	v_pk_mul_f32 v[152:153], v[240:241], v[248:249]
	v_pk_mul_f32 v[146:147], v[146:147], v[138:139]
	v_rcp_f32_e32 v141, v141
	v_rcp_f32_e32 v142, v142
	v_pk_add_f32 v[144:145], v[144:145], 1.0 op_sel_hi:[1,0]
	v_cvt_pk_bf16_f32 v221, v146, v147
	v_pk_mul_f32 v[148:149], v[148:149], v[140:141]
	v_rcp_f32_e32 v143, v143
	v_rcp_f32_e32 v144, v144
	v_cvt_pk_bf16_f32 v225, v148, v149
	v_pk_mul_f32 v[150:151], v[150:151], v[142:143]
	v_rcp_f32_e32 v145, v145
	v_cvt_pk_bf16_f32 v229, v150, v151
	v_pk_mul_f32 v[152:153], v[152:153], v[144:145]
	v_cvt_pk_bf16_f32 v233, v152, v153
	s_mov_b64 s[22:23], exec
	s_mov_b64 exec, s[6:7]
	v_cvt_pk_bf16_f32 v138, v64, v65
	v_cvt_pk_bf16_f32 v139, v66, v67
	v_cvt_pk_bf16_f32 v140, v56, v57
	v_cvt_pk_bf16_f32 v141, v58, v59
	v_cvt_pk_bf16_f32 v142, v76, v77
	v_cvt_pk_bf16_f32 v143, v78, v79
	v_cvt_pk_bf16_f32 v144, v72, v73
	v_cvt_pk_bf16_f32 v145, v74, v75
	global_store_dwordx4 v129, v[138:141], s[10:11]
	global_store_dwordx4 v129, v[142:145], s[10:11] offset:16
	global_store_dwordx4 v129, v[184:187], s[10:11] offset:32
	global_store_dwordx4 v129, v[188:191], s[10:11] offset:48
	s_mov_b64 exec, s[8:9]
	v_cvt_pk_bf16_f32 v146, v4, v5
	v_cvt_pk_bf16_f32 v147, v6, v7
	v_cvt_pk_bf16_f32 v148, v0, v1
	v_cvt_pk_bf16_f32 v149, v2, v3
	v_cvt_pk_bf16_f32 v150, v12, v13
	v_cvt_pk_bf16_f32 v151, v14, v15
	v_cvt_pk_bf16_f32 v152, v8, v9
	v_cvt_pk_bf16_f32 v153, v10, v11
	global_store_dwordx4 v162, v[146:149], s[10:11]
	global_store_dwordx4 v162, v[150:153], s[10:11] offset:16
	global_store_dwordx4 v162, v[192:195], s[10:11] offset:32
	global_store_dwordx4 v162, v[154:157], s[10:11] offset:48
	s_mov_b64 exec, s[56:57]
	global_store_dwordx4 v128, v[218:221], s[52:53]
	s_mov_b64 exec, s[22:23]
	v_add_u32_e32 v133, 0x1600, v128
	v_add_u32_e32 v130, 0x2c00, v128
	v_add_u32_e32 v131, 0x4200, v128
	global_store_dwordx4 v133, v[222:225], s[52:53]
	global_store_dwordx4 v130, v[226:229], s[52:53]
	s_mov_b64 exec, s[58:59]
	global_store_dwordx4 v131, v[230:233], s[52:53]
	s_mov_b64 exec, s[22:23]
	s_mov_b64 s[8:9], 0
